# pool rewrite + hand-written ssdnorm loop (8 units in flight, DPP reductions, double-buffered)
# baseline (speedup 1.0000x reference)
.LBB0_916:
	s_andn2_b64 vcc, exec, s[0:1]
	s_cbranch_vccnz .LBB0_921
	v_mov_b32_e32 v8, v232
	v_readlane_b32 s0, v253, 63
	v_ashrrev_i32_e32 v0, 5, v8
	v_and_b32_e32 v0, -2, v0
	v_add_u32_e32 v0, s0, v0
	s_movk_i32 s0, 0x4400
	v_cmp_gt_i32_e32 vcc, s0, v0
	s_and_saveexec_b64 s[0:1], vcc
	v_readlane_b32 s10, v255, 4
	v_readlane_b32 s11, v255, 5
	s_mov_b32 s9, 0x800000
	v_readlane_b32 s22, v254, 63
	v_readlane_b32 s23, v255, 0
	s_cbranch_execz .LBB0_920
	v_readfirstlane_b32 s22, v0
	v_readlane_b32 s6, v252, 2
	v_readlane_b32 s7, v252, 3
	v_readlane_b32 s23, v255, 20
	v_lshlrev_b32_e32 v2, 4, v233
	v_lshlrev_b32_e32 v3, 5, v233
	v_xor_b32_e32 v4, 16, v233
	v_lshlrev_b32_e32 v4, 2, v4
	s_nop 3
	s_sub_u32 s6, s6, 0x350
	s_subb_u32 s7, s7, 0
	s_load_dwordx2 s[8:9], s[6:7], 0xc0
	s_load_dwordx2 s[10:11], s[6:7], 0x80
	s_lshr_b32 s23, s23, 1
	s_lshl_b32 s23, s23, 13
	s_waitcnt lgkmcnt(0)
	s_add_u32 s10, s10, s23
	s_addc_u32 s11, s11, 0
	global_load_dwordx4 v[8:11], v3, s[10:11]
	global_load_dwordx4 v[12:15], v3, s[10:11] offset:16
	s_add_u32 s10, s10, 0x800
	s_addc_u32 s11, s11, 0
	global_load_dwordx4 v[16:19], v3, s[10:11]
	global_load_dwordx4 v[20:23], v3, s[10:11] offset:16
	s_add_u32 s10, s10, 0x800
	s_addc_u32 s11, s11, 0
	global_load_dwordx4 v[24:27], v3, s[10:11]
	global_load_dwordx4 v[28:31], v3, s[10:11] offset:16
	s_add_u32 s10, s10, 0x800
	s_addc_u32 s11, s11, 0
	global_load_dwordx4 v[32:35], v3, s[10:11]
	global_load_dwordx4 v[36:39], v3, s[10:11] offset:16
	s_add_u32 s24, s8, 0x1a058000
	s_addc_u32 s25, s9, 0
	s_add_u32 s26, s8, 0x1e458000
	s_addc_u32 s27, s9, 0
	s_lshl_b32 s23, s22, 12
	s_add_u32 s6, s24, s23
	s_addc_u32 s7, s25, 0
	global_load_dwordx4 v[50:53], v2, s[6:7] offset:0
	global_load_dwordx4 v[54:57], v2, s[6:7] offset:1024
	global_load_dwordx4 v[58:61], v2, s[6:7] offset:2048
	global_load_dwordx4 v[62:65], v2, s[6:7] offset:3072
	s_add_u32 s6, s6, 0x1000
	s_addc_u32 s7, s7, 0
	global_load_dwordx4 v[66:69], v2, s[6:7] offset:0
	global_load_dwordx4 v[70:73], v2, s[6:7] offset:1024
	global_load_dwordx4 v[74:77], v2, s[6:7] offset:2048
	global_load_dwordx4 v[78:81], v2, s[6:7] offset:3072
	s_add_u32 s10, s22, 4096
	s_cmp_ge_u32 s10, 0x4400
	s_cselect_b32 s10, s22, s10
	s_lshl_b32 s23, s10, 12
	s_add_u32 s6, s24, s23
	s_addc_u32 s7, s25, 0
	global_load_dwordx4 v[82:85], v2, s[6:7] offset:0
	global_load_dwordx4 v[86:89], v2, s[6:7] offset:1024
	global_load_dwordx4 v[90:93], v2, s[6:7] offset:2048
	global_load_dwordx4 v[94:97], v2, s[6:7] offset:3072
	s_add_u32 s6, s6, 0x1000
	s_addc_u32 s7, s7, 0
	global_load_dwordx4 v[98:101], v2, s[6:7] offset:0
	global_load_dwordx4 v[102:105], v2, s[6:7] offset:1024
	global_load_dwordx4 v[106:109], v2, s[6:7] offset:2048
	global_load_dwordx4 v[110:113], v2, s[6:7] offset:3072
	s_waitcnt vmcnt(8)
.Lsn_loop:
	v_lshlrev_b32_e32 v114, 16, v50
	v_and_b32_e32 v115, 0xffff0000, v50
	v_lshlrev_b32_e32 v116, 16, v51
	v_and_b32_e32 v117, 0xffff0000, v51
	v_lshlrev_b32_e32 v118, 16, v52
	v_and_b32_e32 v119, 0xffff0000, v52
	v_lshlrev_b32_e32 v120, 16, v53
	v_and_b32_e32 v121, 0xffff0000, v53
	v_lshlrev_b32_e32 v122, 16, v54
	v_and_b32_e32 v123, 0xffff0000, v54
	v_lshlrev_b32_e32 v124, 16, v55
	v_and_b32_e32 v125, 0xffff0000, v55
	v_lshlrev_b32_e32 v126, 16, v56
	v_and_b32_e32 v127, 0xffff0000, v56
	v_lshlrev_b32_e32 v128, 16, v57
	v_and_b32_e32 v129, 0xffff0000, v57
	v_lshlrev_b32_e32 v130, 16, v58
	v_and_b32_e32 v131, 0xffff0000, v58
	v_lshlrev_b32_e32 v132, 16, v59
	v_and_b32_e32 v133, 0xffff0000, v59
	v_lshlrev_b32_e32 v134, 16, v60
	v_and_b32_e32 v135, 0xffff0000, v60
	v_lshlrev_b32_e32 v136, 16, v61
	v_and_b32_e32 v137, 0xffff0000, v61
	v_lshlrev_b32_e32 v138, 16, v62
	v_and_b32_e32 v139, 0xffff0000, v62
	v_lshlrev_b32_e32 v140, 16, v63
	v_and_b32_e32 v141, 0xffff0000, v63
	v_lshlrev_b32_e32 v142, 16, v64
	v_and_b32_e32 v143, 0xffff0000, v64
	v_lshlrev_b32_e32 v144, 16, v65
	v_and_b32_e32 v145, 0xffff0000, v65
	v_lshlrev_b32_e32 v146, 16, v66
	v_and_b32_e32 v147, 0xffff0000, v66
	v_lshlrev_b32_e32 v148, 16, v67
	v_and_b32_e32 v149, 0xffff0000, v67
	v_lshlrev_b32_e32 v150, 16, v68
	v_and_b32_e32 v151, 0xffff0000, v68
	v_lshlrev_b32_e32 v152, 16, v69
	v_and_b32_e32 v153, 0xffff0000, v69
	v_lshlrev_b32_e32 v154, 16, v70
	v_and_b32_e32 v155, 0xffff0000, v70
	v_lshlrev_b32_e32 v156, 16, v71
	v_and_b32_e32 v157, 0xffff0000, v71
	v_lshlrev_b32_e32 v158, 16, v72
	v_and_b32_e32 v159, 0xffff0000, v72
	v_lshlrev_b32_e32 v160, 16, v73
	v_and_b32_e32 v161, 0xffff0000, v73
	v_lshlrev_b32_e32 v162, 16, v74
	v_and_b32_e32 v163, 0xffff0000, v74
	v_lshlrev_b32_e32 v164, 16, v75
	v_and_b32_e32 v165, 0xffff0000, v75
	v_lshlrev_b32_e32 v166, 16, v76
	v_and_b32_e32 v167, 0xffff0000, v76
	v_lshlrev_b32_e32 v168, 16, v77
	v_and_b32_e32 v169, 0xffff0000, v77
	v_lshlrev_b32_e32 v170, 16, v78
	v_and_b32_e32 v171, 0xffff0000, v78
	v_lshlrev_b32_e32 v172, 16, v79
	v_and_b32_e32 v173, 0xffff0000, v79
	v_lshlrev_b32_e32 v174, 16, v80
	v_and_b32_e32 v175, 0xffff0000, v80
	v_lshlrev_b32_e32 v176, 16, v81
	v_and_b32_e32 v177, 0xffff0000, v81
	v_pk_mul_f32 v[178:179], v[114:115], v[114:115]
	v_pk_mul_f32 v[180:181], v[122:123], v[122:123]
	v_pk_mul_f32 v[182:183], v[130:131], v[130:131]
	v_pk_mul_f32 v[184:185], v[138:139], v[138:139]
	v_pk_mul_f32 v[186:187], v[146:147], v[146:147]
	v_pk_mul_f32 v[188:189], v[154:155], v[154:155]
	v_pk_mul_f32 v[190:191], v[162:163], v[162:163]
	v_pk_mul_f32 v[192:193], v[170:171], v[170:171]
	v_pk_fma_f32 v[178:179], v[116:117], v[116:117], v[178:179]
	v_pk_fma_f32 v[180:181], v[124:125], v[124:125], v[180:181]
	v_pk_fma_f32 v[182:183], v[132:133], v[132:133], v[182:183]
	v_pk_fma_f32 v[184:185], v[140:141], v[140:141], v[184:185]
	v_pk_fma_f32 v[186:187], v[148:149], v[148:149], v[186:187]
	v_pk_fma_f32 v[188:189], v[156:157], v[156:157], v[188:189]
	v_pk_fma_f32 v[190:191], v[164:165], v[164:165], v[190:191]
	v_pk_fma_f32 v[192:193], v[172:173], v[172:173], v[192:193]
	v_pk_fma_f32 v[178:179], v[118:119], v[118:119], v[178:179]
	v_pk_fma_f32 v[180:181], v[126:127], v[126:127], v[180:181]
	v_pk_fma_f32 v[182:183], v[134:135], v[134:135], v[182:183]
	v_pk_fma_f32 v[184:185], v[142:143], v[142:143], v[184:185]
	v_pk_fma_f32 v[186:187], v[150:151], v[150:151], v[186:187]
	v_pk_fma_f32 v[188:189], v[158:159], v[158:159], v[188:189]
	v_pk_fma_f32 v[190:191], v[166:167], v[166:167], v[190:191]
	v_pk_fma_f32 v[192:193], v[174:175], v[174:175], v[192:193]
	v_pk_fma_f32 v[178:179], v[120:121], v[120:121], v[178:179]
	v_pk_fma_f32 v[180:181], v[128:129], v[128:129], v[180:181]
	v_pk_fma_f32 v[182:183], v[136:137], v[136:137], v[182:183]
	v_pk_fma_f32 v[184:185], v[144:145], v[144:145], v[184:185]
	v_pk_fma_f32 v[186:187], v[152:153], v[152:153], v[186:187]
	v_pk_fma_f32 v[188:189], v[160:161], v[160:161], v[188:189]
	v_pk_fma_f32 v[190:191], v[168:169], v[168:169], v[190:191]
	v_pk_fma_f32 v[192:193], v[176:177], v[176:177], v[192:193]
	v_add_f32_e32 v178, v178, v179
	v_add_f32_e32 v180, v180, v181
	v_add_f32_e32 v182, v182, v183
	v_add_f32_e32 v184, v184, v185
	v_add_f32_e32 v186, v186, v187
	v_add_f32_e32 v188, v188, v189
	v_add_f32_e32 v190, v190, v191
	v_add_f32_e32 v192, v192, v193
	v_add_f32_dpp v178, v178, v178 quad_perm:[1,0,3,2] row_mask:0xf bank_mask:0xf
	v_add_f32_dpp v180, v180, v180 quad_perm:[1,0,3,2] row_mask:0xf bank_mask:0xf
	v_add_f32_dpp v182, v182, v182 quad_perm:[1,0,3,2] row_mask:0xf bank_mask:0xf
	v_add_f32_dpp v184, v184, v184 quad_perm:[1,0,3,2] row_mask:0xf bank_mask:0xf
	v_add_f32_dpp v186, v186, v186 quad_perm:[1,0,3,2] row_mask:0xf bank_mask:0xf
	v_add_f32_dpp v188, v188, v188 quad_perm:[1,0,3,2] row_mask:0xf bank_mask:0xf
	v_add_f32_dpp v190, v190, v190 quad_perm:[1,0,3,2] row_mask:0xf bank_mask:0xf
	v_add_f32_dpp v192, v192, v192 quad_perm:[1,0,3,2] row_mask:0xf bank_mask:0xf
	v_add_f32_dpp v178, v178, v178 quad_perm:[2,3,0,1] row_mask:0xf bank_mask:0xf
	v_add_f32_dpp v180, v180, v180 quad_perm:[2,3,0,1] row_mask:0xf bank_mask:0xf
	v_add_f32_dpp v182, v182, v182 quad_perm:[2,3,0,1] row_mask:0xf bank_mask:0xf
	v_add_f32_dpp v184, v184, v184 quad_perm:[2,3,0,1] row_mask:0xf bank_mask:0xf
	v_add_f32_dpp v186, v186, v186 quad_perm:[2,3,0,1] row_mask:0xf bank_mask:0xf
	v_add_f32_dpp v188, v188, v188 quad_perm:[2,3,0,1] row_mask:0xf bank_mask:0xf
	v_add_f32_dpp v190, v190, v190 quad_perm:[2,3,0,1] row_mask:0xf bank_mask:0xf
	v_add_f32_dpp v192, v192, v192 quad_perm:[2,3,0,1] row_mask:0xf bank_mask:0xf
	v_add_f32_dpp v178, v178, v178 row_half_mirror row_mask:0xf bank_mask:0xf
	v_add_f32_dpp v180, v180, v180 row_half_mirror row_mask:0xf bank_mask:0xf
	v_add_f32_dpp v182, v182, v182 row_half_mirror row_mask:0xf bank_mask:0xf
	v_add_f32_dpp v184, v184, v184 row_half_mirror row_mask:0xf bank_mask:0xf
	v_add_f32_dpp v186, v186, v186 row_half_mirror row_mask:0xf bank_mask:0xf
	v_add_f32_dpp v188, v188, v188 row_half_mirror row_mask:0xf bank_mask:0xf
	v_add_f32_dpp v190, v190, v190 row_half_mirror row_mask:0xf bank_mask:0xf
	v_add_f32_dpp v192, v192, v192 row_half_mirror row_mask:0xf bank_mask:0xf
	v_add_f32_dpp v178, v178, v178 row_mirror row_mask:0xf bank_mask:0xf
	v_add_f32_dpp v180, v180, v180 row_mirror row_mask:0xf bank_mask:0xf
	v_add_f32_dpp v182, v182, v182 row_mirror row_mask:0xf bank_mask:0xf
	v_add_f32_dpp v184, v184, v184 row_mirror row_mask:0xf bank_mask:0xf
	v_add_f32_dpp v186, v186, v186 row_mirror row_mask:0xf bank_mask:0xf
	v_add_f32_dpp v188, v188, v188 row_mirror row_mask:0xf bank_mask:0xf
	v_add_f32_dpp v190, v190, v190 row_mirror row_mask:0xf bank_mask:0xf
	v_add_f32_dpp v192, v192, v192 row_mirror row_mask:0xf bank_mask:0xf
	ds_bpermute_b32 v179, v4, v178
	ds_bpermute_b32 v181, v4, v180
	ds_bpermute_b32 v183, v4, v182
	ds_bpermute_b32 v185, v4, v184
	ds_bpermute_b32 v187, v4, v186
	ds_bpermute_b32 v189, v4, v188
	ds_bpermute_b32 v191, v4, v190
	ds_bpermute_b32 v193, v4, v192
	s_waitcnt lgkmcnt(7)
	v_add_f32_e32 v178, v178, v179
	s_waitcnt lgkmcnt(6)
	v_add_f32_e32 v180, v180, v181
	s_waitcnt lgkmcnt(5)
	v_add_f32_e32 v182, v182, v183
	s_waitcnt lgkmcnt(4)
	v_add_f32_e32 v184, v184, v185
	s_waitcnt lgkmcnt(3)
	v_add_f32_e32 v186, v186, v187
	s_waitcnt lgkmcnt(2)
	v_add_f32_e32 v188, v188, v189
	s_waitcnt lgkmcnt(1)
	v_add_f32_e32 v190, v190, v191
	s_waitcnt lgkmcnt(0)
	v_add_f32_e32 v192, v192, v193
	v_fmamk_f32 v178, v178, 0x3b800000, v234
	v_fmamk_f32 v180, v180, 0x3b800000, v234
	v_fmamk_f32 v182, v182, 0x3b800000, v234
	v_fmamk_f32 v184, v184, 0x3b800000, v234
	v_fmamk_f32 v186, v186, 0x3b800000, v234
	v_fmamk_f32 v188, v188, 0x3b800000, v234
	v_fmamk_f32 v190, v190, 0x3b800000, v234
	v_fmamk_f32 v192, v192, 0x3b800000, v234
	v_rsq_f32_e32 v178, v178
	v_rsq_f32_e32 v180, v180
	v_rsq_f32_e32 v182, v182
	v_rsq_f32_e32 v184, v184
	v_rsq_f32_e32 v186, v186
	v_rsq_f32_e32 v188, v188
	v_rsq_f32_e32 v190, v190
	v_rsq_f32_e32 v192, v192
	v_pk_mul_f32 v[114:115], v[114:115], v[178:179] op_sel_hi:[1,0]
	v_pk_mul_f32 v[116:117], v[116:117], v[178:179] op_sel_hi:[1,0]
	v_pk_mul_f32 v[118:119], v[118:119], v[178:179] op_sel_hi:[1,0]
	v_pk_mul_f32 v[120:121], v[120:121], v[178:179] op_sel_hi:[1,0]
	v_pk_mul_f32 v[122:123], v[122:123], v[180:181] op_sel_hi:[1,0]
	v_pk_mul_f32 v[124:125], v[124:125], v[180:181] op_sel_hi:[1,0]
	v_pk_mul_f32 v[126:127], v[126:127], v[180:181] op_sel_hi:[1,0]
	v_pk_mul_f32 v[128:129], v[128:129], v[180:181] op_sel_hi:[1,0]
	v_pk_mul_f32 v[130:131], v[130:131], v[182:183] op_sel_hi:[1,0]
	v_pk_mul_f32 v[132:133], v[132:133], v[182:183] op_sel_hi:[1,0]
	v_pk_mul_f32 v[134:135], v[134:135], v[182:183] op_sel_hi:[1,0]
	v_pk_mul_f32 v[136:137], v[136:137], v[182:183] op_sel_hi:[1,0]
	v_pk_mul_f32 v[138:139], v[138:139], v[184:185] op_sel_hi:[1,0]
	v_pk_mul_f32 v[140:141], v[140:141], v[184:185] op_sel_hi:[1,0]
	v_pk_mul_f32 v[142:143], v[142:143], v[184:185] op_sel_hi:[1,0]
	v_pk_mul_f32 v[144:145], v[144:145], v[184:185] op_sel_hi:[1,0]
	v_pk_mul_f32 v[146:147], v[146:147], v[186:187] op_sel_hi:[1,0]
	v_pk_mul_f32 v[148:149], v[148:149], v[186:187] op_sel_hi:[1,0]
	v_pk_mul_f32 v[150:151], v[150:151], v[186:187] op_sel_hi:[1,0]
	v_pk_mul_f32 v[152:153], v[152:153], v[186:187] op_sel_hi:[1,0]
	v_pk_mul_f32 v[154:155], v[154:155], v[188:189] op_sel_hi:[1,0]
	v_pk_mul_f32 v[156:157], v[156:157], v[188:189] op_sel_hi:[1,0]
	v_pk_mul_f32 v[158:159], v[158:159], v[188:189] op_sel_hi:[1,0]
	v_pk_mul_f32 v[160:161], v[160:161], v[188:189] op_sel_hi:[1,0]
	v_pk_mul_f32 v[162:163], v[162:163], v[190:191] op_sel_hi:[1,0]
	v_pk_mul_f32 v[164:165], v[164:165], v[190:191] op_sel_hi:[1,0]
	v_pk_mul_f32 v[166:167], v[166:167], v[190:191] op_sel_hi:[1,0]
	v_pk_mul_f32 v[168:169], v[168:169], v[190:191] op_sel_hi:[1,0]
	v_pk_mul_f32 v[170:171], v[170:171], v[192:193] op_sel_hi:[1,0]
	v_pk_mul_f32 v[172:173], v[172:173], v[192:193] op_sel_hi:[1,0]
	v_pk_mul_f32 v[174:175], v[174:175], v[192:193] op_sel_hi:[1,0]
	v_pk_mul_f32 v[176:177], v[176:177], v[192:193] op_sel_hi:[1,0]
	v_pk_mul_f32 v[114:115], v[114:115], v[8:9]
	v_pk_mul_f32 v[116:117], v[116:117], v[10:11]
	v_pk_mul_f32 v[118:119], v[118:119], v[12:13]
	v_pk_mul_f32 v[120:121], v[120:121], v[14:15]
	v_pk_mul_f32 v[122:123], v[122:123], v[16:17]
	v_pk_mul_f32 v[124:125], v[124:125], v[18:19]
	v_pk_mul_f32 v[126:127], v[126:127], v[20:21]
	v_pk_mul_f32 v[128:129], v[128:129], v[22:23]
	v_pk_mul_f32 v[130:131], v[130:131], v[24:25]
	v_pk_mul_f32 v[132:133], v[132:133], v[26:27]
	v_pk_mul_f32 v[134:135], v[134:135], v[28:29]
	v_pk_mul_f32 v[136:137], v[136:137], v[30:31]
	v_pk_mul_f32 v[138:139], v[138:139], v[32:33]
	v_pk_mul_f32 v[140:141], v[140:141], v[34:35]
	v_pk_mul_f32 v[142:143], v[142:143], v[36:37]
	v_pk_mul_f32 v[144:145], v[144:145], v[38:39]
	v_pk_mul_f32 v[146:147], v[146:147], v[8:9]
	v_pk_mul_f32 v[148:149], v[148:149], v[10:11]
	v_pk_mul_f32 v[150:151], v[150:151], v[12:13]
	v_pk_mul_f32 v[152:153], v[152:153], v[14:15]
	v_pk_mul_f32 v[154:155], v[154:155], v[16:17]
	v_pk_mul_f32 v[156:157], v[156:157], v[18:19]
	v_pk_mul_f32 v[158:159], v[158:159], v[20:21]
	v_pk_mul_f32 v[160:161], v[160:161], v[22:23]
	v_pk_mul_f32 v[162:163], v[162:163], v[24:25]
	v_pk_mul_f32 v[164:165], v[164:165], v[26:27]
	v_pk_mul_f32 v[166:167], v[166:167], v[28:29]
	v_pk_mul_f32 v[168:169], v[168:169], v[30:31]
	v_pk_mul_f32 v[170:171], v[170:171], v[32:33]
	v_pk_mul_f32 v[172:173], v[172:173], v[34:35]
	v_pk_mul_f32 v[174:175], v[174:175], v[36:37]
	v_pk_mul_f32 v[176:177], v[176:177], v[38:39]
	v_cvt_pk_bf16_f32 v50, v114, v115
	v_cvt_pk_bf16_f32 v51, v116, v117
	v_cvt_pk_bf16_f32 v52, v118, v119
	v_cvt_pk_bf16_f32 v53, v120, v121
	v_cvt_pk_bf16_f32 v54, v122, v123
	v_cvt_pk_bf16_f32 v55, v124, v125
	v_cvt_pk_bf16_f32 v56, v126, v127
	v_cvt_pk_bf16_f32 v57, v128, v129
	v_cvt_pk_bf16_f32 v58, v130, v131
	v_cvt_pk_bf16_f32 v59, v132, v133
	v_cvt_pk_bf16_f32 v60, v134, v135
	v_cvt_pk_bf16_f32 v61, v136, v137
	v_cvt_pk_bf16_f32 v62, v138, v139
	v_cvt_pk_bf16_f32 v63, v140, v141
	v_cvt_pk_bf16_f32 v64, v142, v143
	v_cvt_pk_bf16_f32 v65, v144, v145
	v_cvt_pk_bf16_f32 v66, v146, v147
	v_cvt_pk_bf16_f32 v67, v148, v149
	v_cvt_pk_bf16_f32 v68, v150, v151
	v_cvt_pk_bf16_f32 v69, v152, v153
	v_cvt_pk_bf16_f32 v70, v154, v155
	v_cvt_pk_bf16_f32 v71, v156, v157
	v_cvt_pk_bf16_f32 v72, v158, v159
	v_cvt_pk_bf16_f32 v73, v160, v161
	v_cvt_pk_bf16_f32 v74, v162, v163
	v_cvt_pk_bf16_f32 v75, v164, v165
	v_cvt_pk_bf16_f32 v76, v166, v167
	v_cvt_pk_bf16_f32 v77, v168, v169
	v_cvt_pk_bf16_f32 v78, v170, v171
	v_cvt_pk_bf16_f32 v79, v172, v173
	v_cvt_pk_bf16_f32 v80, v174, v175
	v_cvt_pk_bf16_f32 v81, v176, v177
	s_lshl_b32 s23, s22, 12
	s_add_u32 s6, s26, s23
	s_addc_u32 s7, s27, 0
	global_store_dwordx4 v2, v[50:53], s[6:7] offset:0
	global_store_dwordx4 v2, v[54:57], s[6:7] offset:1024
	global_store_dwordx4 v2, v[58:61], s[6:7] offset:2048
	global_store_dwordx4 v2, v[62:65], s[6:7] offset:3072
	s_add_u32 s6, s6, 0x1000
	s_addc_u32 s7, s7, 0
	global_store_dwordx4 v2, v[66:69], s[6:7] offset:0
	global_store_dwordx4 v2, v[70:73], s[6:7] offset:1024
	global_store_dwordx4 v2, v[74:77], s[6:7] offset:2048
	global_store_dwordx4 v2, v[78:81], s[6:7] offset:3072
	s_add_u32 s10, s22, 8192
	s_cmp_ge_u32 s10, 0x4400
	s_cselect_b32 s10, s22, s10
	s_lshl_b32 s23, s10, 12
	s_add_u32 s6, s24, s23
	s_addc_u32 s7, s25, 0
	global_load_dwordx4 v[50:53], v2, s[6:7] offset:0
	global_load_dwordx4 v[54:57], v2, s[6:7] offset:1024
	global_load_dwordx4 v[58:61], v2, s[6:7] offset:2048
	global_load_dwordx4 v[62:65], v2, s[6:7] offset:3072
	s_add_u32 s6, s6, 0x1000
	s_addc_u32 s7, s7, 0
	global_load_dwordx4 v[66:69], v2, s[6:7] offset:0
	global_load_dwordx4 v[70:73], v2, s[6:7] offset:1024
	global_load_dwordx4 v[74:77], v2, s[6:7] offset:2048
	global_load_dwordx4 v[78:81], v2, s[6:7] offset:3072
	s_waitcnt vmcnt(16)
	s_add_u32 s10, s22, 4096
	s_cmp_ge_u32 s10, 0x4400
	s_cbranch_scc1 .Lsn_end
	v_lshlrev_b32_e32 v114, 16, v82
	v_and_b32_e32 v115, 0xffff0000, v82
	v_lshlrev_b32_e32 v116, 16, v83
	v_and_b32_e32 v117, 0xffff0000, v83
	v_lshlrev_b32_e32 v118, 16, v84
	v_and_b32_e32 v119, 0xffff0000, v84
	v_lshlrev_b32_e32 v120, 16, v85
	v_and_b32_e32 v121, 0xffff0000, v85
	v_lshlrev_b32_e32 v122, 16, v86
	v_and_b32_e32 v123, 0xffff0000, v86
	v_lshlrev_b32_e32 v124, 16, v87
	v_and_b32_e32 v125, 0xffff0000, v87
	v_lshlrev_b32_e32 v126, 16, v88
	v_and_b32_e32 v127, 0xffff0000, v88
	v_lshlrev_b32_e32 v128, 16, v89
	v_and_b32_e32 v129, 0xffff0000, v89
	v_lshlrev_b32_e32 v130, 16, v90
	v_and_b32_e32 v131, 0xffff0000, v90
	v_lshlrev_b32_e32 v132, 16, v91
	v_and_b32_e32 v133, 0xffff0000, v91
	v_lshlrev_b32_e32 v134, 16, v92
	v_and_b32_e32 v135, 0xffff0000, v92
	v_lshlrev_b32_e32 v136, 16, v93
	v_and_b32_e32 v137, 0xffff0000, v93
	v_lshlrev_b32_e32 v138, 16, v94
	v_and_b32_e32 v139, 0xffff0000, v94
	v_lshlrev_b32_e32 v140, 16, v95
	v_and_b32_e32 v141, 0xffff0000, v95
	v_lshlrev_b32_e32 v142, 16, v96
	v_and_b32_e32 v143, 0xffff0000, v96
	v_lshlrev_b32_e32 v144, 16, v97
	v_and_b32_e32 v145, 0xffff0000, v97
	v_lshlrev_b32_e32 v146, 16, v98
	v_and_b32_e32 v147, 0xffff0000, v98
	v_lshlrev_b32_e32 v148, 16, v99
	v_and_b32_e32 v149, 0xffff0000, v99
	v_lshlrev_b32_e32 v150, 16, v100
	v_and_b32_e32 v151, 0xffff0000, v100
	v_lshlrev_b32_e32 v152, 16, v101
	v_and_b32_e32 v153, 0xffff0000, v101
	v_lshlrev_b32_e32 v154, 16, v102
	v_and_b32_e32 v155, 0xffff0000, v102
	v_lshlrev_b32_e32 v156, 16, v103
	v_and_b32_e32 v157, 0xffff0000, v103
	v_lshlrev_b32_e32 v158, 16, v104
	v_and_b32_e32 v159, 0xffff0000, v104
	v_lshlrev_b32_e32 v160, 16, v105
	v_and_b32_e32 v161, 0xffff0000, v105
	v_lshlrev_b32_e32 v162, 16, v106
	v_and_b32_e32 v163, 0xffff0000, v106
	v_lshlrev_b32_e32 v164, 16, v107
	v_and_b32_e32 v165, 0xffff0000, v107
	v_lshlrev_b32_e32 v166, 16, v108
	v_and_b32_e32 v167, 0xffff0000, v108
	v_lshlrev_b32_e32 v168, 16, v109
	v_and_b32_e32 v169, 0xffff0000, v109
	v_lshlrev_b32_e32 v170, 16, v110
	v_and_b32_e32 v171, 0xffff0000, v110
	v_lshlrev_b32_e32 v172, 16, v111
	v_and_b32_e32 v173, 0xffff0000, v111
	v_lshlrev_b32_e32 v174, 16, v112
	v_and_b32_e32 v175, 0xffff0000, v112
	v_lshlrev_b32_e32 v176, 16, v113
	v_and_b32_e32 v177, 0xffff0000, v113
	v_pk_mul_f32 v[178:179], v[114:115], v[114:115]
	v_pk_mul_f32 v[180:181], v[122:123], v[122:123]
	v_pk_mul_f32 v[182:183], v[130:131], v[130:131]
	v_pk_mul_f32 v[184:185], v[138:139], v[138:139]
	v_pk_mul_f32 v[186:187], v[146:147], v[146:147]
	v_pk_mul_f32 v[188:189], v[154:155], v[154:155]
	v_pk_mul_f32 v[190:191], v[162:163], v[162:163]
	v_pk_mul_f32 v[192:193], v[170:171], v[170:171]
	v_pk_fma_f32 v[178:179], v[116:117], v[116:117], v[178:179]
	v_pk_fma_f32 v[180:181], v[124:125], v[124:125], v[180:181]
	v_pk_fma_f32 v[182:183], v[132:133], v[132:133], v[182:183]
	v_pk_fma_f32 v[184:185], v[140:141], v[140:141], v[184:185]
	v_pk_fma_f32 v[186:187], v[148:149], v[148:149], v[186:187]
	v_pk_fma_f32 v[188:189], v[156:157], v[156:157], v[188:189]
	v_pk_fma_f32 v[190:191], v[164:165], v[164:165], v[190:191]
	v_pk_fma_f32 v[192:193], v[172:173], v[172:173], v[192:193]
	v_pk_fma_f32 v[178:179], v[118:119], v[118:119], v[178:179]
	v_pk_fma_f32 v[180:181], v[126:127], v[126:127], v[180:181]
	v_pk_fma_f32 v[182:183], v[134:135], v[134:135], v[182:183]
	v_pk_fma_f32 v[184:185], v[142:143], v[142:143], v[184:185]
	v_pk_fma_f32 v[186:187], v[150:151], v[150:151], v[186:187]
	v_pk_fma_f32 v[188:189], v[158:159], v[158:159], v[188:189]
	v_pk_fma_f32 v[190:191], v[166:167], v[166:167], v[190:191]
	v_pk_fma_f32 v[192:193], v[174:175], v[174:175], v[192:193]
	v_pk_fma_f32 v[178:179], v[120:121], v[120:121], v[178:179]
	v_pk_fma_f32 v[180:181], v[128:129], v[128:129], v[180:181]
	v_pk_fma_f32 v[182:183], v[136:137], v[136:137], v[182:183]
	v_pk_fma_f32 v[184:185], v[144:145], v[144:145], v[184:185]
	v_pk_fma_f32 v[186:187], v[152:153], v[152:153], v[186:187]
	v_pk_fma_f32 v[188:189], v[160:161], v[160:161], v[188:189]
	v_pk_fma_f32 v[190:191], v[168:169], v[168:169], v[190:191]
	v_pk_fma_f32 v[192:193], v[176:177], v[176:177], v[192:193]
	v_add_f32_e32 v178, v178, v179
	v_add_f32_e32 v180, v180, v181
	v_add_f32_e32 v182, v182, v183
	v_add_f32_e32 v184, v184, v185
	v_add_f32_e32 v186, v186, v187
	v_add_f32_e32 v188, v188, v189
	v_add_f32_e32 v190, v190, v191
	v_add_f32_e32 v192, v192, v193
	v_add_f32_dpp v178, v178, v178 quad_perm:[1,0,3,2] row_mask:0xf bank_mask:0xf
	v_add_f32_dpp v180, v180, v180 quad_perm:[1,0,3,2] row_mask:0xf bank_mask:0xf
	v_add_f32_dpp v182, v182, v182 quad_perm:[1,0,3,2] row_mask:0xf bank_mask:0xf
	v_add_f32_dpp v184, v184, v184 quad_perm:[1,0,3,2] row_mask:0xf bank_mask:0xf
	v_add_f32_dpp v186, v186, v186 quad_perm:[1,0,3,2] row_mask:0xf bank_mask:0xf
	v_add_f32_dpp v188, v188, v188 quad_perm:[1,0,3,2] row_mask:0xf bank_mask:0xf
	v_add_f32_dpp v190, v190, v190 quad_perm:[1,0,3,2] row_mask:0xf bank_mask:0xf
	v_add_f32_dpp v192, v192, v192 quad_perm:[1,0,3,2] row_mask:0xf bank_mask:0xf
	v_add_f32_dpp v178, v178, v178 quad_perm:[2,3,0,1] row_mask:0xf bank_mask:0xf
	v_add_f32_dpp v180, v180, v180 quad_perm:[2,3,0,1] row_mask:0xf bank_mask:0xf
	v_add_f32_dpp v182, v182, v182 quad_perm:[2,3,0,1] row_mask:0xf bank_mask:0xf
	v_add_f32_dpp v184, v184, v184 quad_perm:[2,3,0,1] row_mask:0xf bank_mask:0xf
	v_add_f32_dpp v186, v186, v186 quad_perm:[2,3,0,1] row_mask:0xf bank_mask:0xf
	v_add_f32_dpp v188, v188, v188 quad_perm:[2,3,0,1] row_mask:0xf bank_mask:0xf
	v_add_f32_dpp v190, v190, v190 quad_perm:[2,3,0,1] row_mask:0xf bank_mask:0xf
	v_add_f32_dpp v192, v192, v192 quad_perm:[2,3,0,1] row_mask:0xf bank_mask:0xf
	v_add_f32_dpp v178, v178, v178 row_half_mirror row_mask:0xf bank_mask:0xf
	v_add_f32_dpp v180, v180, v180 row_half_mirror row_mask:0xf bank_mask:0xf
	v_add_f32_dpp v182, v182, v182 row_half_mirror row_mask:0xf bank_mask:0xf
	v_add_f32_dpp v184, v184, v184 row_half_mirror row_mask:0xf bank_mask:0xf
	v_add_f32_dpp v186, v186, v186 row_half_mirror row_mask:0xf bank_mask:0xf
	v_add_f32_dpp v188, v188, v188 row_half_mirror row_mask:0xf bank_mask:0xf
	v_add_f32_dpp v190, v190, v190 row_half_mirror row_mask:0xf bank_mask:0xf
	v_add_f32_dpp v192, v192, v192 row_half_mirror row_mask:0xf bank_mask:0xf
	v_add_f32_dpp v178, v178, v178 row_mirror row_mask:0xf bank_mask:0xf
	v_add_f32_dpp v180, v180, v180 row_mirror row_mask:0xf bank_mask:0xf
	v_add_f32_dpp v182, v182, v182 row_mirror row_mask:0xf bank_mask:0xf
	v_add_f32_dpp v184, v184, v184 row_mirror row_mask:0xf bank_mask:0xf
	v_add_f32_dpp v186, v186, v186 row_mirror row_mask:0xf bank_mask:0xf
	v_add_f32_dpp v188, v188, v188 row_mirror row_mask:0xf bank_mask:0xf
	v_add_f32_dpp v190, v190, v190 row_mirror row_mask:0xf bank_mask:0xf
	v_add_f32_dpp v192, v192, v192 row_mirror row_mask:0xf bank_mask:0xf
	ds_bpermute_b32 v179, v4, v178
	ds_bpermute_b32 v181, v4, v180
	ds_bpermute_b32 v183, v4, v182
	ds_bpermute_b32 v185, v4, v184
	ds_bpermute_b32 v187, v4, v186
	ds_bpermute_b32 v189, v4, v188
	ds_bpermute_b32 v191, v4, v190
	ds_bpermute_b32 v193, v4, v192
	s_waitcnt lgkmcnt(7)
	v_add_f32_e32 v178, v178, v179
	s_waitcnt lgkmcnt(6)
	v_add_f32_e32 v180, v180, v181
	s_waitcnt lgkmcnt(5)
	v_add_f32_e32 v182, v182, v183
	s_waitcnt lgkmcnt(4)
	v_add_f32_e32 v184, v184, v185
	s_waitcnt lgkmcnt(3)
	v_add_f32_e32 v186, v186, v187
	s_waitcnt lgkmcnt(2)
	v_add_f32_e32 v188, v188, v189
	s_waitcnt lgkmcnt(1)
	v_add_f32_e32 v190, v190, v191
	s_waitcnt lgkmcnt(0)
	v_add_f32_e32 v192, v192, v193
	v_fmamk_f32 v178, v178, 0x3b800000, v234
	v_fmamk_f32 v180, v180, 0x3b800000, v234
	v_fmamk_f32 v182, v182, 0x3b800000, v234
	v_fmamk_f32 v184, v184, 0x3b800000, v234
	v_fmamk_f32 v186, v186, 0x3b800000, v234
	v_fmamk_f32 v188, v188, 0x3b800000, v234
	v_fmamk_f32 v190, v190, 0x3b800000, v234
	v_fmamk_f32 v192, v192, 0x3b800000, v234
	v_rsq_f32_e32 v178, v178
	v_rsq_f32_e32 v180, v180
	v_rsq_f32_e32 v182, v182
	v_rsq_f32_e32 v184, v184
	v_rsq_f32_e32 v186, v186
	v_rsq_f32_e32 v188, v188
	v_rsq_f32_e32 v190, v190
	v_rsq_f32_e32 v192, v192
	v_pk_mul_f32 v[114:115], v[114:115], v[178:179] op_sel_hi:[1,0]
	v_pk_mul_f32 v[116:117], v[116:117], v[178:179] op_sel_hi:[1,0]
	v_pk_mul_f32 v[118:119], v[118:119], v[178:179] op_sel_hi:[1,0]
	v_pk_mul_f32 v[120:121], v[120:121], v[178:179] op_sel_hi:[1,0]
	v_pk_mul_f32 v[122:123], v[122:123], v[180:181] op_sel_hi:[1,0]
	v_pk_mul_f32 v[124:125], v[124:125], v[180:181] op_sel_hi:[1,0]
	v_pk_mul_f32 v[126:127], v[126:127], v[180:181] op_sel_hi:[1,0]
	v_pk_mul_f32 v[128:129], v[128:129], v[180:181] op_sel_hi:[1,0]
	v_pk_mul_f32 v[130:131], v[130:131], v[182:183] op_sel_hi:[1,0]
	v_pk_mul_f32 v[132:133], v[132:133], v[182:183] op_sel_hi:[1,0]
	v_pk_mul_f32 v[134:135], v[134:135], v[182:183] op_sel_hi:[1,0]
	v_pk_mul_f32 v[136:137], v[136:137], v[182:183] op_sel_hi:[1,0]
	v_pk_mul_f32 v[138:139], v[138:139], v[184:185] op_sel_hi:[1,0]
	v_pk_mul_f32 v[140:141], v[140:141], v[184:185] op_sel_hi:[1,0]
	v_pk_mul_f32 v[142:143], v[142:143], v[184:185] op_sel_hi:[1,0]
	v_pk_mul_f32 v[144:145], v[144:145], v[184:185] op_sel_hi:[1,0]
	v_pk_mul_f32 v[146:147], v[146:147], v[186:187] op_sel_hi:[1,0]
	v_pk_mul_f32 v[148:149], v[148:149], v[186:187] op_sel_hi:[1,0]
	v_pk_mul_f32 v[150:151], v[150:151], v[186:187] op_sel_hi:[1,0]
	v_pk_mul_f32 v[152:153], v[152:153], v[186:187] op_sel_hi:[1,0]
	v_pk_mul_f32 v[154:155], v[154:155], v[188:189] op_sel_hi:[1,0]
	v_pk_mul_f32 v[156:157], v[156:157], v[188:189] op_sel_hi:[1,0]
	v_pk_mul_f32 v[158:159], v[158:159], v[188:189] op_sel_hi:[1,0]
	v_pk_mul_f32 v[160:161], v[160:161], v[188:189] op_sel_hi:[1,0]
	v_pk_mul_f32 v[162:163], v[162:163], v[190:191] op_sel_hi:[1,0]
	v_pk_mul_f32 v[164:165], v[164:165], v[190:191] op_sel_hi:[1,0]
	v_pk_mul_f32 v[166:167], v[166:167], v[190:191] op_sel_hi:[1,0]
	v_pk_mul_f32 v[168:169], v[168:169], v[190:191] op_sel_hi:[1,0]
	v_pk_mul_f32 v[170:171], v[170:171], v[192:193] op_sel_hi:[1,0]
	v_pk_mul_f32 v[172:173], v[172:173], v[192:193] op_sel_hi:[1,0]
	v_pk_mul_f32 v[174:175], v[174:175], v[192:193] op_sel_hi:[1,0]
	v_pk_mul_f32 v[176:177], v[176:177], v[192:193] op_sel_hi:[1,0]
	v_pk_mul_f32 v[114:115], v[114:115], v[8:9]
	v_pk_mul_f32 v[116:117], v[116:117], v[10:11]
	v_pk_mul_f32 v[118:119], v[118:119], v[12:13]
	v_pk_mul_f32 v[120:121], v[120:121], v[14:15]
	v_pk_mul_f32 v[122:123], v[122:123], v[16:17]
	v_pk_mul_f32 v[124:125], v[124:125], v[18:19]
	v_pk_mul_f32 v[126:127], v[126:127], v[20:21]
	v_pk_mul_f32 v[128:129], v[128:129], v[22:23]
	v_pk_mul_f32 v[130:131], v[130:131], v[24:25]
	v_pk_mul_f32 v[132:133], v[132:133], v[26:27]
	v_pk_mul_f32 v[134:135], v[134:135], v[28:29]
	v_pk_mul_f32 v[136:137], v[136:137], v[30:31]
	v_pk_mul_f32 v[138:139], v[138:139], v[32:33]
	v_pk_mul_f32 v[140:141], v[140:141], v[34:35]
	v_pk_mul_f32 v[142:143], v[142:143], v[36:37]
	v_pk_mul_f32 v[144:145], v[144:145], v[38:39]
	v_pk_mul_f32 v[146:147], v[146:147], v[8:9]
	v_pk_mul_f32 v[148:149], v[148:149], v[10:11]
	v_pk_mul_f32 v[150:151], v[150:151], v[12:13]
	v_pk_mul_f32 v[152:153], v[152:153], v[14:15]
	v_pk_mul_f32 v[154:155], v[154:155], v[16:17]
	v_pk_mul_f32 v[156:157], v[156:157], v[18:19]
	v_pk_mul_f32 v[158:159], v[158:159], v[20:21]
	v_pk_mul_f32 v[160:161], v[160:161], v[22:23]
	v_pk_mul_f32 v[162:163], v[162:163], v[24:25]
	v_pk_mul_f32 v[164:165], v[164:165], v[26:27]
	v_pk_mul_f32 v[166:167], v[166:167], v[28:29]
	v_pk_mul_f32 v[168:169], v[168:169], v[30:31]
	v_pk_mul_f32 v[170:171], v[170:171], v[32:33]
	v_pk_mul_f32 v[172:173], v[172:173], v[34:35]
	v_pk_mul_f32 v[174:175], v[174:175], v[36:37]
	v_pk_mul_f32 v[176:177], v[176:177], v[38:39]
	v_cvt_pk_bf16_f32 v82, v114, v115
	v_cvt_pk_bf16_f32 v83, v116, v117
	v_cvt_pk_bf16_f32 v84, v118, v119
	v_cvt_pk_bf16_f32 v85, v120, v121
	v_cvt_pk_bf16_f32 v86, v122, v123
	v_cvt_pk_bf16_f32 v87, v124, v125
	v_cvt_pk_bf16_f32 v88, v126, v127
	v_cvt_pk_bf16_f32 v89, v128, v129
	v_cvt_pk_bf16_f32 v90, v130, v131
	v_cvt_pk_bf16_f32 v91, v132, v133
	v_cvt_pk_bf16_f32 v92, v134, v135
	v_cvt_pk_bf16_f32 v93, v136, v137
	v_cvt_pk_bf16_f32 v94, v138, v139
	v_cvt_pk_bf16_f32 v95, v140, v141
	v_cvt_pk_bf16_f32 v96, v142, v143
	v_cvt_pk_bf16_f32 v97, v144, v145
	v_cvt_pk_bf16_f32 v98, v146, v147
	v_cvt_pk_bf16_f32 v99, v148, v149
	v_cvt_pk_bf16_f32 v100, v150, v151
	v_cvt_pk_bf16_f32 v101, v152, v153
	v_cvt_pk_bf16_f32 v102, v154, v155
	v_cvt_pk_bf16_f32 v103, v156, v157
	v_cvt_pk_bf16_f32 v104, v158, v159
	v_cvt_pk_bf16_f32 v105, v160, v161
	v_cvt_pk_bf16_f32 v106, v162, v163
	v_cvt_pk_bf16_f32 v107, v164, v165
	v_cvt_pk_bf16_f32 v108, v166, v167
	v_cvt_pk_bf16_f32 v109, v168, v169
	v_cvt_pk_bf16_f32 v110, v170, v171
	v_cvt_pk_bf16_f32 v111, v172, v173
	v_cvt_pk_bf16_f32 v112, v174, v175
	v_cvt_pk_bf16_f32 v113, v176, v177
	s_lshl_b32 s23, s10, 12
	s_add_u32 s6, s26, s23
	s_addc_u32 s7, s27, 0
	global_store_dwordx4 v2, v[82:85], s[6:7] offset:0
	global_store_dwordx4 v2, v[86:89], s[6:7] offset:1024
	global_store_dwordx4 v2, v[90:93], s[6:7] offset:2048
	global_store_dwordx4 v2, v[94:97], s[6:7] offset:3072
	s_add_u32 s6, s6, 0x1000
	s_addc_u32 s7, s7, 0
	global_store_dwordx4 v2, v[98:101], s[6:7] offset:0
	global_store_dwordx4 v2, v[102:105], s[6:7] offset:1024
	global_store_dwordx4 v2, v[106:109], s[6:7] offset:2048
	global_store_dwordx4 v2, v[110:113], s[6:7] offset:3072
	s_add_u32 s10, s22, 12288
	s_cmp_ge_u32 s10, 0x4400
	s_cselect_b32 s10, s22, s10
	s_lshl_b32 s23, s10, 12
	s_add_u32 s6, s24, s23
	s_addc_u32 s7, s25, 0
	global_load_dwordx4 v[82:85], v2, s[6:7] offset:0
	global_load_dwordx4 v[86:89], v2, s[6:7] offset:1024
	global_load_dwordx4 v[90:93], v2, s[6:7] offset:2048
	global_load_dwordx4 v[94:97], v2, s[6:7] offset:3072
	s_add_u32 s6, s6, 0x1000
	s_addc_u32 s7, s7, 0
	global_load_dwordx4 v[98:101], v2, s[6:7] offset:0
	global_load_dwordx4 v[102:105], v2, s[6:7] offset:1024
	global_load_dwordx4 v[106:109], v2, s[6:7] offset:2048
	global_load_dwordx4 v[110:113], v2, s[6:7] offset:3072
	s_waitcnt vmcnt(16)
	s_add_u32 s22, s22, 8192
	s_cmp_lt_u32 s22, 0x4400
	s_cbranch_scc1 .Lsn_loop
.Lsn_end:
	s_waitcnt vmcnt(0)
.LBB0_920:
	s_or_b64 exec, exec, s[0:1]
